# setup: lora transpose loop no longer waits for its own previous stores before issuing the next loads
# baseline (speedup 1.0000x reference)
; __device__ __forceinline__ bf16_t f2bf(float f) { return (bf16_t)(pack2(f, 0.f) & 0xffffu); }
; __device__ __forceinline__ void phase_setup(const Params& p, unsigned char* smem) {
;     ...
;         for (int i = tid; i < 8192; i += 256) {
;           int idx = tt * 8192 + i;
;           int arr = idx >> 16, e = idx & 65535;
;           int ld = e >> 14, rem = e & 16383, n = rem >> 6, k = rem & 63;
;           const float* src = arr ? p.rwkv_a_up : p.rwkv_w_up;
;           bf16_t* dst = arr ? p.AupT : p.WupT;
;           dst[e] = f2bf(src[((size_t)ld * 64 + k) * 256 + n]);
;         }
.LBB0_1339:
	s_nop 0
	v_add_u32_e32 v28, s66, v15
	v_add_u32_e32 v29, s65, v14
	v_lshlrev_b32_e32 v21, 8, v15
	v_lshlrev_b32_e32 v33, 8, v14
	v_mov_b32_e32 v16, s7
	v_mov_b32_e32 v18, s3
	v_mov_b32_e32 v27, s5
	v_mov_b32_e32 v30, s1
	v_and_b32_e32 v36, 0x3f00, v21
	v_and_b32_e32 v33, 0x3f00, v33
	v_and_b32_e32 v37, 0xc000, v28
	v_and_b32_e32 v38, 0xc000, v29
	v_cmp_gt_u32_e32 vcc, s27, v28
	v_cmp_gt_u32_e64 s[54:55], s27, v29
	v_mov_b32_e32 v20, s6
	v_mov_b32_e32 v26, s2
	v_mov_b32_e32 v31, s4
	v_mov_b32_e32 v32, s0
	v_lshrrev_b32_e32 v34, 6, v28
	v_lshrrev_b32_e32 v35, 6, v29
	v_cndmask_b32_e32 v21, v16, v18, vcc
	v_cndmask_b32_e64 v27, v27, v30, s[54:55]
	v_or_b32_e32 v16, v37, v36
	v_or_b32_e32 v30, v38, v33
	v_mov_b32_e32 v17, v164
	v_cndmask_b32_e32 v20, v20, v26, vcc
	v_cndmask_b32_e64 v26, v31, v32, s[54:55]
	v_or_b32_sdwa v18, v16, v34 dst_sel:DWORD dst_unused:UNUSED_PAD src0_sel:DWORD src1_sel:BYTE_0
	v_or_b32_sdwa v16, v30, v35 dst_sel:DWORD dst_unused:UNUSED_PAD src0_sel:DWORD src1_sel:BYTE_0
	v_mov_b32_e32 v19, v164
	v_lshl_add_u64 v[16:17], v[16:17], 2, v[26:27]
	v_lshl_add_u64 v[18:19], v[18:19], 2, v[20:21]
	global_load_dword v30, v[16:17], off
	global_load_dword v31, v[18:19], off
	v_mov_b32_e32 v20, s15
	v_mov_b32_e32 v21, s11
	v_mov_b32_e32 v26, s14
	v_mov_b32_e32 v27, s10
	v_mov_b32_e32 v32, s13
	v_mov_b32_e32 v33, s9
	v_mov_b32_e32 v34, s12
	v_mov_b32_e32 v35, s8
	v_add_u32_e32 v1, -2, v1
	v_mov_b32_e32 v17, v164
	v_mov_b32_e32 v19, v164
	v_lshlrev_b32_sdwa v16, v190, v29 dst_sel:DWORD dst_unused:UNUSED_PAD src0_sel:DWORD src1_sel:WORD_0
	v_lshlrev_b32_sdwa v18, v190, v28 dst_sel:DWORD dst_unused:UNUSED_PAD src0_sel:DWORD src1_sel:WORD_0
	v_cmp_eq_u32_e64 s[56:57], 0, v1
	v_cndmask_b32_e32 v21, v20, v21, vcc
	v_cndmask_b32_e32 v20, v26, v27, vcc
	v_cndmask_b32_e64 v27, v32, v33, s[54:55]
	v_cndmask_b32_e64 v26, v34, v35, s[54:55]
	v_add_u32_e32 v15, 0x200, v15
	v_add_u32_e32 v14, 0x200, v14
	s_or_b64 s[62:63], s[56:57], s[62:63]
	v_lshl_add_u64 v[16:17], v[26:27], 0, v[16:17]
	v_lshl_add_u64 v[18:19], v[20:21], 0, v[18:19]
	s_waitcnt vmcnt(0)
	v_cvt_pk_bf16_f32 v20, v30, v31
	global_store_short v[16:17], v20, off
	global_store_short_d16_hi v[18:19], v20, off
	s_andn2_b64 exec, exec, s[62:63]
	s_cbranch_execnz .LBB0_1339
	s_or_b64 exec, exec, s[62:63]
	s_orn2_b64 s[54:55], s[52:53], exec
	v_mov_b32_e32 v14, v23
